# DMA ring: dropped two redundant per-unit barriers
# baseline (speedup 1.0000x reference)
; #define LAS __attribute__((address_space(3)))
; #define AT_LOAD(K0, K1, V0, V1, T) do { const size_t e_ = (size_t)(128 * (T) + sr) * 64 + sc; \
;         K0 = *(const bf16x8*)(kcp + e_); V0 = *(const bf16x8*)(vcp + e_); K1 = *(const bf16x8*)(kcp + e_ + 64 * 64); V1 = *(const bf16x8*)(vcp + e_ + 64 * 64); } while (0)
; #define AT_STORE(K0, K1, V0, V1, BUF) do { *(LAS bf16x8*)(lds + AT_K + (BUF) * AT_KB + kst0) = K0; *(LAS bf16x8*)(lds + AT_K + (BUF) * AT_KB + kst1) = K1; \
;         *(LAS bf16x8*)(lds + AT_V + (BUF) * AT_VB + vst0) = V0; *(LAS bf16x8*)(lds + AT_V + (BUF) * AT_VB + vst1) = V1; } while (0)
; template <int VAR>
; __device__ __forceinline__ void attn_unit(const Args& a, int l, int b, int h, int qrow0  , bool ctxu, const bf16* Z, bf16* Y, LAS unsigned char* lds) {
;     ...
;     AT_LOAD(ka0, ka1, va0, va1, 0); AT_LOAD(kb0, kb1, vb0_, vb1_, 1); AT_STORE(ka0, ka1, va0, va1, 0);
;     const LAS unsigned char* Kb0 = lds + AT_K + comp * 64;
;     for (int t = 0; t < NT; t += 2) {
;         __syncthreads();
;         if (t + 2 < NT) AT_LOAD(ka0, ka1, va0, va1, t + 2);
.Lat_noprio:
	s_waitcnt lgkmcnt(0)
	s_add_u32 m0, s51, 0x0
	s_nop 0
	global_load_lds_dwordx4 v128, s[36:37]
	s_add_u32 m0, s51, 0x2000
	s_nop 0
	global_load_lds_dwordx4 v129, s[36:37]
	s_add_u32 m0, s51, 0x4000
	s_nop 0
	global_load_lds_dwordx4 v130, s[48:49]
	s_add_u32 m0, s51, 0x6000
	s_nop 0
	global_load_lds_dwordx4 v131, s[48:49]
	s_add_u32 s36, s36, 0x4000
	s_addc_u32 s37, s37, 0
	s_add_u32 s48, s48, 0x4000
	s_addc_u32 s49, s49, 0
	s_add_u32 m0, s51, 0x8000
	s_nop 0
	global_load_lds_dwordx4 v128, s[36:37]
	s_add_u32 m0, s51, 0xa000
	s_nop 0
	global_load_lds_dwordx4 v129, s[36:37]
	s_add_u32 m0, s51, 0xc000
	s_nop 0
	global_load_lds_dwordx4 v130, s[48:49]
	s_add_u32 m0, s51, 0xe000
	s_nop 0
	global_load_lds_dwordx4 v131, s[48:49]
	s_add_u32 s36, s36, 0x4000
	s_addc_u32 s37, s37, 0
	s_add_u32 s48, s48, 0x4000
	s_addc_u32 s49, s49, 0
	s_waitcnt vmcnt(4)
	s_barrier
	s_add_u32 m0, s51, 0x11800
	s_nop 0
	global_load_lds_dwordx4 v128, s[36:37]
	s_add_u32 m0, s51, 0x13800
	s_nop 0
	global_load_lds_dwordx4 v129, s[36:37]
	s_add_u32 m0, s51, 0x15800
	s_nop 0
	global_load_lds_dwordx4 v130, s[48:49]
	s_add_u32 m0, s51, 0x17800
	s_nop 0
	global_load_lds_dwordx4 v131, s[48:49]
	s_add_u32 s36, s36, 0x4000
	s_addc_u32 s37, s37, 0
	s_add_u32 s48, s48, 0x4000
	s_addc_u32 s49, s49, 0
	ds_read_b128 v[48:51], v132 offset:0
	ds_read_b128 v[52:55], v133 offset:0
	ds_read_b128 v[56:59], v132 offset:4096
	ds_read_b128 v[60:63], v133 offset:4096

; __device__ __forceinline__ int crow(int r, int hi) { return (r & 3) + 8 * (r >> 2) + 4 * hi; }
; template <int VAR>
; __device__ __forceinline__ void attn_unit(const Args& a, int l, int b, int h, int qrow0  , bool ctxu, const bf16* Z, bf16* Y, LAS unsigned char* lds) {
;     ...
;     if (comp == 1) {
; #pragma unroll
;         for (int r = 0; r < 16; ++r) { const int qr = crow(r, hi); const float il = lam * __builtin_amdgcn_rcpf(lacc[r]); stg[qr * 64 + r32] = o0[r] * il; stg[qr * 64 + 32 + r32] = o1[r] * il; }
;     }
;     __syncthreads();
;     if (comp == 0) {
; #pragma unroll
;         for (int r = 0; r < 16; ++r) { const int qr = crow(r, hi); const float il = __builtin_amdgcn_rcpf(lacc[r]); o0[r] = o0[r] * il - stg[qr * 64 + r32]; o1[r] = o1[r] * il - stg[qr * 64 + 32 + r32]; }
.Lat_backz5:
	v_exp_f32_e32 v96, v96
	v_exp_f32_e32 v97, v97
	v_exp_f32_e32 v98, v98
	v_exp_f32_e32 v99, v99
	v_exp_f32_e32 v100, v100
	v_exp_f32_e32 v101, v101
	v_exp_f32_e32 v102, v102
	v_exp_f32_e32 v103, v103
	v_cvt_pk_bf16_f32 v40, v96, v97
	v_cvt_pk_bf16_f32 v41, v98, v99
	v_cvt_pk_bf16_f32 v42, v100, v101
	v_cvt_pk_bf16_f32 v43, v102, v103
	v_pk_add_f32 v[32:33], v[32:33], v[96:97]
	v_pk_add_f32 v[32:33], v[32:33], v[98:99]
	v_pk_add_f32 v[32:33], v[32:33], v[100:101]
	v_pk_add_f32 v[32:33], v[32:33], v[102:103]
	s_waitcnt lgkmcnt(12)
	v_mfma_f32_32x32x16_bf16 v[0:15], v[40:43], v[168:171], v[0:15]
	v_exp_f32_e32 v104, v104
	v_exp_f32_e32 v105, v105
	v_exp_f32_e32 v106, v106
	v_exp_f32_e32 v107, v107
	v_mfma_f32_32x32x16_bf16 v[16:31], v[40:43], v[172:175], v[16:31]
	v_exp_f32_e32 v108, v108
	v_exp_f32_e32 v109, v109
	v_exp_f32_e32 v110, v110
	v_exp_f32_e32 v111, v111
	v_cvt_pk_bf16_f32 v44, v104, v105
	v_cvt_pk_bf16_f32 v45, v106, v107
	v_cvt_pk_bf16_f32 v46, v108, v109
	v_cvt_pk_bf16_f32 v47, v110, v111
	v_pk_add_f32 v[32:33], v[32:33], v[104:105]
	v_pk_add_f32 v[32:33], v[32:33], v[106:107]
	v_pk_add_f32 v[32:33], v[32:33], v[108:109]
	v_pk_add_f32 v[32:33], v[32:33], v[110:111]
	s_waitcnt lgkmcnt(8)
	v_mfma_f32_32x32x16_bf16 v[0:15], v[44:47], v[176:179], v[0:15]
	v_exp_f32_e32 v112, v112
	v_exp_f32_e32 v113, v113
	v_exp_f32_e32 v114, v114
	v_exp_f32_e32 v115, v115
	v_mfma_f32_32x32x16_bf16 v[16:31], v[44:47], v[180:183], v[16:31]
	v_exp_f32_e32 v116, v116
	v_exp_f32_e32 v117, v117
	v_exp_f32_e32 v118, v118
	v_exp_f32_e32 v119, v119
	v_cvt_pk_bf16_f32 v40, v112, v113
	v_cvt_pk_bf16_f32 v41, v114, v115
	v_cvt_pk_bf16_f32 v42, v116, v117
	v_cvt_pk_bf16_f32 v43, v118, v119
	v_pk_add_f32 v[32:33], v[32:33], v[112:113]
	v_pk_add_f32 v[32:33], v[32:33], v[114:115]
	v_pk_add_f32 v[32:33], v[32:33], v[116:117]
	v_pk_add_f32 v[32:33], v[32:33], v[118:119]
	s_waitcnt lgkmcnt(4)
	v_mfma_f32_32x32x16_bf16 v[0:15], v[40:43], v[184:187], v[0:15]
	v_exp_f32_e32 v120, v120
	v_exp_f32_e32 v121, v121
	v_exp_f32_e32 v122, v122
	v_exp_f32_e32 v123, v123
	v_mfma_f32_32x32x16_bf16 v[16:31], v[40:43], v[188:191], v[16:31]
	v_exp_f32_e32 v124, v124
	v_exp_f32_e32 v125, v125
	v_exp_f32_e32 v126, v126
	v_exp_f32_e32 v127, v127
	v_cvt_pk_bf16_f32 v44, v120, v121
	v_cvt_pk_bf16_f32 v45, v122, v123
	v_cvt_pk_bf16_f32 v46, v124, v125
	v_cvt_pk_bf16_f32 v47, v126, v127
	v_pk_add_f32 v[32:33], v[32:33], v[120:121]
	v_pk_add_f32 v[32:33], v[32:33], v[122:123]
	v_pk_add_f32 v[32:33], v[32:33], v[124:125]
	v_pk_add_f32 v[32:33], v[32:33], v[126:127]
	s_waitcnt vmcnt(0)
	s_waitcnt lgkmcnt(0)
	s_barrier
	ds_read_b128 v[48:51], v132 offset:0
	ds_read_b128 v[52:55], v133 offset:0
	ds_read_b128 v[56:59], v132 offset:4096
	ds_read_b128 v[60:63], v133 offset:4096
	v_mfma_f32_32x32x16_bf16 v[0:15], v[44:47], v[192:195], v[0:15]
	v_mfma_f32_32x32x16_bf16 v[16:31], v[44:47], v[196:199], v[16:31]
	v_add_f32_e32 v34, v32, v33
	v_add_u32_e32 v36, s31, v216
	v_mov_b32_e32 v35, v34
	s_nop 1
	v_permlane32_swap_b32_e32 v34, v35
	v_add_f32_e32 v37, v34, v35
	s_waitcnt lgkmcnt(0)
	ds_write_b32 v232, v37
	s_waitcnt lgkmcnt(0)
	v_mov_b32_e32 v48, v36
	ds_read_b128 v[32:35], v48 offset:0
	ds_read_b128 v[36:39], v48 offset:32
	ds_read_b128 v[40:43], v48 offset:64
	ds_read_b128 v[44:47], v48 offset:96
	s_waitcnt vmcnt(0) lgkmcnt(0)
	s_setprio 0
	s_branch .LBB0_459
